# ssd3 per-half staging: 12 serialized loads batched (9 in flight + 3 recycled), LDS writes behind counted vmcnt
# speedup vs baseline: 1.0142x; 1.0118x over previous
.LBB0_39:
	v_readlane_b32 s6, v255, 8
	s_xor_b64 s[26:27], s[0:1], -1
	s_lshl_b32 s0, s4, 7
	v_readlane_b32 s7, v255, 9
	v_mov_b32_e32 v73, v179
	s_barrier
	s_or_b32 s66, s6, s0
	v_readlane_b32 s6, v255, 18
	v_lshlrev_b32_e32 v66, 4, v73
	v_ashrrev_i32_e32 v74, 4, v73
	v_and_b32_e32 v66, 0xf0, v66
	v_mov_b32_e32 v67, v1
	v_readlane_b32 s7, v255, 19
	v_ashrrev_i32_e32 v75, 31, v74
	v_add_u32_e32 v72, 32, v66
	v_lshl_add_u64 v[70:71], s[6:7], 0, v[66:67]
	v_lshl_add_u64 v[66:67], s[66:67], 0, v[74:75]
	v_lshlrev_b64 v[66:67], 13, v[66:67]
	v_lshl_add_u64 v[66:67], v[70:71], 0, v[66:67]
	global_load_dwordx4 v[200:203], v[66:67], off
	s_movk_i32 s1, 0x110
	v_mad_u64_u32 v[74:75], s[6:7], v74, s1, v[72:73]
	v_mov_b32_e32 v226, v74
	s_cmp_lt_u32 s4, s35
	s_cselect_b64 s[54:55], -1, 0
	s_cmp_eq_u32 s4, s35
	s_cselect_b64 s[36:37], -1, 0
	s_cmp_gt_u32 s4, s35
	s_movk_i32 s28, 0x110
	s_cselect_b64 s[38:39], -1, 0
	v_or_b32_e32 v84, s0, v150
	v_add_u32_e32 v66, 0x200, v73
	v_ashrrev_i32_e32 v74, 4, v66
	v_ashrrev_i32_e32 v75, 31, v74
	v_lshl_add_u64 v[66:67], s[66:67], 0, v[74:75]
	v_lshlrev_b64 v[66:67], 13, v[66:67]
	v_lshl_add_u64 v[66:67], v[70:71], 0, v[66:67]
	global_load_dwordx4 v[204:207], v[66:67], off
	v_add_u32_e32 v66, 0x400, v73
	v_ashrrev_i32_e32 v74, 4, v66
	v_ashrrev_i32_e32 v75, 31, v74
	v_lshl_add_u64 v[66:67], s[66:67], 0, v[74:75]
	v_lshlrev_b64 v[66:67], 13, v[66:67]
	v_lshl_add_u64 v[66:67], v[70:71], 0, v[66:67]
	global_load_dwordx4 v[208:211], v[66:67], off
	v_add_u32_e32 v66, 0x600, v73
	v_ashrrev_i32_e32 v74, 4, v66
	v_ashrrev_i32_e32 v75, 31, v74
	v_lshl_add_u64 v[66:67], s[66:67], 0, v[74:75]
	v_lshlrev_b64 v[66:67], 13, v[66:67]
	v_lshl_add_u64 v[66:67], v[70:71], 0, v[66:67]
	global_load_dwordx4 v[212:215], v[66:67], off
	v_mov_b32_e32 v68, v179
	v_mov_b32_e32 v67, s67
	v_and_b32_e32 v70, 0x7f, v68
	v_or_b32_e32 v66, s66, v70
	v_ashrrev_i32_e32 v68, 1, v68
	v_lshlrev_b64 v[66:67], 13, v[66:67]
	v_and_b32_e32 v68, 0xffffffc0, v68
	v_lshl_add_u64 v[66:67], s[2:3], 0, v[66:67]
	v_ashrrev_i32_e32 v69, 31, v68
	v_lshl_add_u64 v[66:67], v[68:69], 1, v[66:67]
	v_mul_lo_u32 v72, v68, s1
	v_lshlrev_b32_e32 v73, 1, v70
	global_load_dwordx4 v[130:133], v[66:67], off
	v_readlane_b32 s1, v254, 4
	s_mov_b32 s66, 0
	s_nop 0
	v_add3_u32 v74, s1, v72, v73
	v_add3_u32 v72, s1, v73, v72
	global_load_dwordx4 v[134:137], v[66:67], off offset:16
	global_load_dwordx4 v[138:141], v[66:67], off offset:32
	global_load_dwordx4 v[192:195], v[66:67], off offset:48
	global_load_dwordx4 v[222:225], v[66:67], off offset:64
	s_waitcnt vmcnt(8)
	ds_write_b128 v226, v[200:203] offset:34816
	global_load_dwordx4 v[200:203], v[66:67], off offset:80
	s_waitcnt vmcnt(8)
	ds_write_b128 v226, v[204:207] offset:43520
	global_load_dwordx4 v[204:207], v[66:67], off offset:96
	s_waitcnt vmcnt(8)
	ds_write_b128 v226, v[208:211] offset:52224
	global_load_dwordx4 v[208:211], v[66:67], off offset:112
	s_waitcnt vmcnt(8)
	ds_write_b128 v226, v[212:215] offset:60928
	s_waitcnt vmcnt(7)
	ds_write_b16 v74, v130
	ds_write_b16_d16_hi v72, v130 offset:272
	ds_write_b16 v72, v131 offset:544
	ds_write_b16_d16_hi v72, v131 offset:816
	ds_write_b16 v72, v132 offset:1088
	ds_write_b16_d16_hi v72, v132 offset:1360
	ds_write_b16 v74, v133 offset:1632
	ds_write_b16_d16_hi v72, v133 offset:1904
	s_waitcnt vmcnt(6)
	ds_write_b16 v72, v134 offset:2176
	ds_write_b16_d16_hi v72, v134 offset:2448
	ds_write_b16 v74, v135 offset:2720
	ds_write_b16_d16_hi v72, v135 offset:2992
	ds_write_b16 v72, v136 offset:3264
	ds_write_b16_d16_hi v72, v136 offset:3536
	ds_write_b16 v74, v137 offset:3808
	ds_write_b16_d16_hi v72, v137 offset:4080
	s_waitcnt vmcnt(5)
	ds_write_b16 v72, v138 offset:4352
	ds_write_b16_d16_hi v72, v138 offset:4624
	ds_write_b16 v74, v139 offset:4896
	ds_write_b16_d16_hi v72, v139 offset:5168
	ds_write_b16 v72, v140 offset:5440
	ds_write_b16_d16_hi v72, v140 offset:5712
	ds_write_b16 v74, v141 offset:5984
	ds_write_b16_d16_hi v72, v141 offset:6256
	s_waitcnt vmcnt(4)
	ds_write_b16 v72, v192 offset:6528
	ds_write_b16_d16_hi v72, v192 offset:6800
	ds_write_b16 v74, v193 offset:7072
	ds_write_b16_d16_hi v72, v193 offset:7344
	ds_write_b16 v72, v194 offset:7616
	ds_write_b16_d16_hi v72, v194 offset:7888
	ds_write_b16 v74, v195 offset:8160
	ds_write_b16_d16_hi v72, v195 offset:8432
	s_waitcnt vmcnt(3)
	ds_write_b16 v72, v222 offset:8704
	ds_write_b16_d16_hi v72, v222 offset:8976
	ds_write_b16 v74, v223 offset:9248
	ds_write_b16_d16_hi v72, v223 offset:9520
	ds_write_b16 v72, v224 offset:9792
	ds_write_b16_d16_hi v72, v224 offset:10064
	ds_write_b16 v74, v225 offset:10336
	ds_write_b16_d16_hi v72, v225 offset:10608
	s_waitcnt vmcnt(2)
	ds_write_b16 v72, v200 offset:10880
	ds_write_b16_d16_hi v72, v200 offset:11152
	ds_write_b16 v74, v201 offset:11424
	ds_write_b16_d16_hi v72, v201 offset:11696
	ds_write_b16 v72, v202 offset:11968
	ds_write_b16_d16_hi v72, v202 offset:12240
	ds_write_b16 v74, v203 offset:12512
	ds_write_b16_d16_hi v72, v203 offset:12784
	s_waitcnt vmcnt(1)
	ds_write_b16 v72, v204 offset:13056
	ds_write_b16_d16_hi v72, v204 offset:13328
	ds_write_b16 v74, v205 offset:13600
	ds_write_b16_d16_hi v72, v205 offset:13872
	ds_write_b16 v72, v206 offset:14144
	ds_write_b16_d16_hi v72, v206 offset:14416
	ds_write_b16 v74, v207 offset:14688
	ds_write_b16_d16_hi v72, v207 offset:14960
	s_waitcnt vmcnt(0)
	ds_write_b16 v72, v208 offset:15232
	ds_write_b16_d16_hi v72, v208 offset:15504
	ds_write_b16 v74, v209 offset:15776
	ds_write_b16_d16_hi v72, v209 offset:16048
	ds_write_b16 v72, v210 offset:16320
	ds_write_b16_d16_hi v72, v210 offset:16592
	ds_write_b16 v74, v211 offset:16864
	ds_write_b16_d16_hi v72, v211 offset:17136
	s_waitcnt lgkmcnt(0)
	s_barrier
	s_branch .LBB0_42
